# grid barrier: replicated release counter, pollers spread over all 16 copies by workgroup id (16 pollers per address)
# speedup vs baseline: 1.0115x; 1.0027x over previous
.Lxb_wait_0:
	buffer_inv sc1
	v_readlane_b32 s16, v252, 5
	s_nop 3
	s_and_b32 s16, s16, 15
	s_lshl_b32 s16, s16, 8
	s_add_u32 s14, s14, s16
	s_addc_u32 s15, s15, 0
	s_mov_b32 s16, 0
